# SwiGLU epilogue: issue the 8 row-scale loads together and wait once instead of 8 serialized load+vmcnt(0) round trips
# speedup vs baseline: 1.0131x; 1.0131x over previous
.LBB0_741:
	s_and_b64 vcc, exec, s[56:57]
	s_cbranch_vccz .LBB0_740
	v_lshl_add_u32 v144, s15, 8, v170
	v_ashrrev_i32_e32 v145, 31, v144
	s_waitcnt lgkmcnt(0)
	v_lshl_add_u64 v[128:129], v[144:145], 3, s[96:97]
	global_load_dwordx2 v[128:129], v[128:129], off
	s_flbit_i32_b32 s1, 0
	s_min_u32 s2, s1, 32
	s_sub_i32 s1, 32, s2
	v_add_u32_e32 v142, 16, v144
	v_ashrrev_i32_e32 v143, 31, v142
	v_lshl_add_u64 v[222:223], v[142:143], 3, s[96:97]
	global_load_dwordx2 v[222:223], v[222:223], off
	v_add_u32_e32 v140, 32, v144
	v_ashrrev_i32_e32 v141, 31, v140
	v_lshl_add_u64 v[224:225], v[140:141], 3, s[96:97]
	global_load_dwordx2 v[224:225], v[224:225], off
	v_add_u32_e32 v138, 48, v144
	v_ashrrev_i32_e32 v139, 31, v138
	v_lshl_add_u64 v[226:227], v[138:139], 3, s[96:97]
	global_load_dwordx2 v[226:227], v[226:227], off
	v_add_u32_e32 v136, 0x80, v144
	v_ashrrev_i32_e32 v137, 31, v136
	v_lshl_add_u64 v[228:229], v[136:137], 3, s[96:97]
	global_load_dwordx2 v[228:229], v[228:229], off
	v_add_u32_e32 v134, 0x90, v144
	v_ashrrev_i32_e32 v135, 31, v134
	v_lshl_add_u64 v[230:231], v[134:135], 3, s[96:97]
	global_load_dwordx2 v[230:231], v[230:231], off
	v_add_u32_e32 v232, 0xa0, v144
	v_ashrrev_i32_e32 v233, 31, v232
	v_lshl_add_u64 v[232:233], v[232:233], 3, s[96:97]
	global_load_dwordx2 v[232:233], v[232:233], off
	v_add_u32_e32 v234, 0xb0, v144
	v_ashrrev_i32_e32 v235, 31, v234
	v_lshl_add_u64 v[132:133], v[234:235], 3, s[96:97]
	global_load_dwordx2 v[132:133], v[132:133], off
	v_pk_mul_f32 v[126:127], v[126:127], v[122:123]
	v_pk_mul_f32 v[118:119], v[118:119], v[114:115]
	v_pk_mul_f32 v[110:111], v[110:111], v[106:107]
	v_pk_mul_f32 v[102:103], v[102:103], v[98:99]
	v_pk_mul_f32 v[94:95], v[94:95], v[90:91]
	v_pk_mul_f32 v[86:87], v[86:87], v[82:83]
	v_pk_mul_f32 v[78:79], v[78:79], v[74:75]
	v_pk_mul_f32 v[70:71], v[70:71], v[66:67]
	v_pk_mul_f32 v[62:63], v[62:63], v[58:59]
	v_pk_mul_f32 v[54:55], v[54:55], v[50:51]
	v_pk_mul_f32 v[46:47], v[46:47], v[42:43]
	v_pk_mul_f32 v[38:39], v[38:39], v[34:35]
	v_pk_mul_f32 v[30:31], v[30:31], v[26:27]
	v_pk_mul_f32 v[22:23], v[22:23], v[18:19]
	v_pk_mul_f32 v[14:15], v[14:15], v[10:11]
	v_pk_mul_f32 v[6:7], v[6:7], v[2:3]
	s_waitcnt vmcnt(0)
	v_mov_b32_e32 v156, v129
	v_lshlrev_b64 v[130:131], s2, v[156:157]
	v_min_u32_e32 v129, 1, v130
	v_or_b32_e32 v129, v131, v129
	v_cvt_f32_u32_e32 v129, v129
	v_cvt_f32_u32_e32 v128, v128
	v_ldexp_f32 v129, v129, s1
	v_mul_f32_e32 v153, 0x43800000, v129
	v_fmac_f32_e32 v153, 0x33800000, v128
	v_fmamk_f32 v153, v153, 0x3a800000, v194
	v_rsq_f32_e32 v153, v153
	v_mov_b32_e32 v156, v223
	v_lshlrev_b64 v[130:131], s2, v[156:157]
	v_min_u32_e32 v129, 1, v130
	v_or_b32_e32 v129, v131, v129
	v_cvt_f32_u32_e32 v129, v129
	v_cvt_f32_u32_e32 v128, v222
	v_ldexp_f32 v129, v129, s1
	v_mul_f32_e32 v152, 0x43800000, v129
	v_fmac_f32_e32 v152, 0x33800000, v128
	v_mov_b32_e32 v156, v225
	v_lshlrev_b64 v[130:131], s2, v[156:157]
	v_min_u32_e32 v129, 1, v130
	v_or_b32_e32 v129, v131, v129
	v_cvt_f32_u32_e32 v129, v129
	v_cvt_f32_u32_e32 v128, v224
	v_ldexp_f32 v129, v129, s1
	v_mul_f32_e32 v151, 0x43800000, v129
	v_fmac_f32_e32 v151, 0x33800000, v128
	v_mov_b32_e32 v156, v227
	v_lshlrev_b64 v[130:131], s2, v[156:157]
	v_min_u32_e32 v129, 1, v130
	v_or_b32_e32 v129, v131, v129
	v_cvt_f32_u32_e32 v129, v129
	v_cvt_f32_u32_e32 v128, v226
	v_ldexp_f32 v129, v129, s1
	v_mul_f32_e32 v150, 0x43800000, v129
	v_fmac_f32_e32 v150, 0x33800000, v128
	v_mov_b32_e32 v156, v229
	v_lshlrev_b64 v[130:131], s2, v[156:157]
	v_min_u32_e32 v129, 1, v130
	v_or_b32_e32 v129, v131, v129
	v_cvt_f32_u32_e32 v129, v129
	v_cvt_f32_u32_e32 v128, v228
	v_ldexp_f32 v129, v129, s1
	v_mul_f32_e32 v149, 0x43800000, v129
	v_fmac_f32_e32 v149, 0x33800000, v128
	v_mov_b32_e32 v156, v231
	v_lshlrev_b64 v[130:131], s2, v[156:157]
	v_min_u32_e32 v129, 1, v130
	v_or_b32_e32 v129, v131, v129
	v_cvt_f32_u32_e32 v129, v129
	v_cvt_f32_u32_e32 v128, v230
	v_ldexp_f32 v129, v129, s1
	v_mul_f32_e32 v148, 0x43800000, v129
	v_fmac_f32_e32 v148, 0x33800000, v128
	v_mov_b32_e32 v156, v233
	v_lshlrev_b64 v[130:131], s2, v[156:157]
	v_min_u32_e32 v129, 1, v130
	v_or_b32_e32 v129, v131, v129
	v_cvt_f32_u32_e32 v129, v129
	v_cvt_f32_u32_e32 v128, v232
	v_ldexp_f32 v129, v129, s1
	v_mul_f32_e32 v146, 0x43800000, v129
	v_fmac_f32_e32 v146, 0x33800000, v128
	v_add_u32_e32 v130, 0xa0, v144
	v_ashrrev_i32_e32 v131, 31, v130
	v_add_u32_e32 v128, 0xb0, v144
	v_ashrrev_i32_e32 v129, 31, v128
	v_mov_b32_e32 v156, v133
	v_lshlrev_b64 v[154:155], s2, v[156:157]
	v_min_u32_e32 v133, 1, v154
	v_mul_f32_e32 v154, 0xbfb8aa3b, v153
	v_pk_mul_f32 v[170:171], v[120:121], v[154:155] op_sel_hi:[1,0]
	v_pk_mul_f32 v[122:123], v[122:123], v[154:155] op_sel_hi:[1,0]
	v_exp_f32_e32 v170, v170
	v_exp_f32_e32 v171, v171
	v_exp_f32_e32 v122, v122
	v_exp_f32_e32 v123, v123
	v_mul_f32_e32 v156, v153, v153
	v_pk_add_f32 v[170:171], v[170:171], 1.0 op_sel_hi:[1,0]
	v_pk_mul_f32 v[120:121], v[124:125], v[120:121]
	v_pk_add_f32 v[122:123], v[122:123], 1.0 op_sel_hi:[1,0]
	v_rcp_f32_e32 v170, v170
	v_rcp_f32_e32 v171, v171
	v_rcp_f32_e32 v122, v122
	v_rcp_f32_e32 v123, v123
	v_or_b32_e32 v133, v155, v133
	v_pk_mul_f32 v[124:125], v[156:157], v[170:171] op_sel_hi:[0,1]
	v_pk_mul_f32 v[120:121], v[120:121], v[124:125]
	v_pk_mul_f32 v[122:123], v[156:157], v[122:123] op_sel_hi:[0,1]
	v_pk_mul_f32 v[122:123], v[126:127], v[122:123]
	v_cvt_pk_bf16_f32 v120, v120, v121
	v_cvt_f32_u32_e32 v133, v133
	v_cvt_pk_bf16_f32 v121, v122, v123
	v_pk_mul_f32 v[122:123], v[112:113], v[154:155] op_sel_hi:[1,0]
	v_pk_mul_f32 v[112:113], v[116:117], v[112:113]
	v_exp_f32_e32 v122, v122
	v_exp_f32_e32 v123, v123
	v_cvt_f32_u32_e32 v132, v132
	v_ldexp_f32 v133, v133, s1
	s_lshl_b32 s1, s48, 7
	v_pk_add_f32 v[122:123], v[122:123], 1.0 op_sel_hi:[1,0]
	v_mul_f32_e32 v147, 0x43800000, v133
	v_rcp_f32_e32 v122, v122
	v_rcp_f32_e32 v123, v123
	s_or_b32 s1, s1, s58
	v_fmac_f32_e32 v147, 0x33800000, v132
	v_lshl_add_u32 v132, v221, 3, s1
	v_pk_mul_f32 v[116:117], v[156:157], v[122:123] op_sel_hi:[0,1]
	v_pk_mul_f32 v[112:113], v[112:113], v[116:117]
	v_ashrrev_i32_e32 v133, 31, v132
	v_cvt_pk_bf16_f32 v122, v112, v113
	v_pk_mul_f32 v[112:113], v[114:115], v[154:155] op_sel_hi:[1,0]
	v_lshl_add_u64 v[132:133], v[132:133], 1, s[76:77]
	v_exp_f32_e32 v112, v112
	v_exp_f32_e32 v113, v113
	s_nop 0
	v_pk_add_f32 v[112:113], v[112:113], 1.0 op_sel_hi:[1,0]
	s_nop 0
	v_rcp_f32_e32 v112, v112
	v_rcp_f32_e32 v113, v113
	s_nop 0
	v_pk_mul_f32 v[112:113], v[156:157], v[112:113] op_sel_hi:[0,1]
	v_pk_mul_f32 v[112:113], v[118:119], v[112:113]
	s_nop 0
	v_cvt_pk_bf16_f32 v123, v112, v113
	v_mad_u64_u32 v[112:113], s[6:7], v144, s14, 0
	v_mov_b32_e32 v114, v113
	v_mad_u64_u32 v[114:115], s[6:7], v145, s14, v[114:115]
	v_mov_b32_e32 v113, v114
	v_lshl_add_u64 v[112:113], v[112:113], 1, v[132:133]
	global_store_dwordx4 v[112:113], v[120:123], off
	v_fmamk_f32 v112, v152, 0x3a800000, v194
	v_rsq_f32_e32 v113, v112
	s_nop 0
	v_mul_f32_e32 v112, 0xbfb8aa3b, v113
	v_pk_mul_f32 v[116:117], v[104:105], v[112:113] op_sel_hi:[1,0]
	v_pk_mul_f32 v[106:107], v[106:107], v[112:113] op_sel_hi:[1,0]
	v_exp_f32_e32 v116, v116
	v_exp_f32_e32 v117, v117
	v_exp_f32_e32 v106, v106
	v_exp_f32_e32 v107, v107
	v_mul_f32_e32 v114, v113, v113
	v_pk_add_f32 v[116:117], v[116:117], 1.0 op_sel_hi:[1,0]
	v_pk_mul_f32 v[104:105], v[108:109], v[104:105]
	v_pk_add_f32 v[106:107], v[106:107], 1.0 op_sel_hi:[1,0]
	v_rcp_f32_e32 v116, v116
	v_rcp_f32_e32 v117, v117
	v_rcp_f32_e32 v106, v106
	v_rcp_f32_e32 v107, v107
	v_pk_mul_f32 v[108:109], v[114:115], v[116:117] op_sel_hi:[0,1]
	v_pk_mul_f32 v[104:105], v[104:105], v[108:109]
	v_pk_mul_f32 v[106:107], v[114:115], v[106:107] op_sel_hi:[0,1]
	v_pk_mul_f32 v[106:107], v[110:111], v[106:107]
	v_cvt_pk_bf16_f32 v104, v104, v105
	s_nop 0
	v_cvt_pk_bf16_f32 v105, v106, v107
	v_pk_mul_f32 v[106:107], v[96:97], v[112:113] op_sel_hi:[1,0]
	v_pk_mul_f32 v[96:97], v[100:101], v[96:97]
	v_exp_f32_e32 v106, v106
	v_exp_f32_e32 v107, v107
	s_nop 0
	v_pk_add_f32 v[106:107], v[106:107], 1.0 op_sel_hi:[1,0]
	s_nop 0
	v_rcp_f32_e32 v106, v106
	v_rcp_f32_e32 v107, v107
	s_nop 0
	v_pk_mul_f32 v[100:101], v[114:115], v[106:107] op_sel_hi:[0,1]
	v_pk_mul_f32 v[96:97], v[96:97], v[100:101]
	s_nop 0
	v_cvt_pk_bf16_f32 v106, v96, v97
	v_pk_mul_f32 v[96:97], v[98:99], v[112:113] op_sel_hi:[1,0]
	s_nop 0
	v_exp_f32_e32 v96, v96
	v_exp_f32_e32 v97, v97
	s_nop 0
	v_pk_add_f32 v[96:97], v[96:97], 1.0 op_sel_hi:[1,0]
	s_nop 0
	v_rcp_f32_e32 v96, v96
	v_rcp_f32_e32 v97, v97
	s_nop 0
	v_pk_mul_f32 v[96:97], v[114:115], v[96:97] op_sel_hi:[0,1]
	v_pk_mul_f32 v[96:97], v[102:103], v[96:97]
	s_nop 0
	v_cvt_pk_bf16_f32 v107, v96, v97
	v_mad_u64_u32 v[96:97], s[6:7], v142, s14, 0
	v_mov_b32_e32 v98, v97
	v_mad_u64_u32 v[98:99], s[6:7], v143, s14, v[98:99]
	v_mov_b32_e32 v97, v98
	v_lshl_add_u64 v[96:97], v[96:97], 1, v[132:133]
	global_store_dwordx4 v[96:97], v[104:107], off
	v_fmamk_f32 v96, v151, 0x3a800000, v194
	v_rsq_f32_e32 v97, v96
	s_nop 0
	v_mul_f32_e32 v96, 0xbfb8aa3b, v97
	v_pk_mul_f32 v[100:101], v[88:89], v[96:97] op_sel_hi:[1,0]
	v_pk_mul_f32 v[90:91], v[90:91], v[96:97] op_sel_hi:[1,0]
	v_exp_f32_e32 v100, v100
	v_exp_f32_e32 v101, v101
	v_exp_f32_e32 v90, v90
	v_exp_f32_e32 v91, v91
	v_mul_f32_e32 v98, v97, v97
	v_pk_add_f32 v[100:101], v[100:101], 1.0 op_sel_hi:[1,0]
	v_pk_mul_f32 v[88:89], v[92:93], v[88:89]
	v_pk_add_f32 v[90:91], v[90:91], 1.0 op_sel_hi:[1,0]
	v_rcp_f32_e32 v100, v100
	v_rcp_f32_e32 v101, v101
	v_rcp_f32_e32 v90, v90
	v_rcp_f32_e32 v91, v91
	v_pk_mul_f32 v[92:93], v[98:99], v[100:101] op_sel_hi:[0,1]
	v_pk_mul_f32 v[88:89], v[88:89], v[92:93]
	v_pk_mul_f32 v[90:91], v[98:99], v[90:91] op_sel_hi:[0,1]
	v_pk_mul_f32 v[90:91], v[94:95], v[90:91]
	v_cvt_pk_bf16_f32 v88, v88, v89
	s_nop 0
	v_cvt_pk_bf16_f32 v89, v90, v91
	v_pk_mul_f32 v[90:91], v[80:81], v[96:97] op_sel_hi:[1,0]
	v_pk_mul_f32 v[80:81], v[84:85], v[80:81]
	v_exp_f32_e32 v90, v90
	v_exp_f32_e32 v91, v91
	s_nop 0
	v_pk_add_f32 v[90:91], v[90:91], 1.0 op_sel_hi:[1,0]
	s_nop 0
	v_rcp_f32_e32 v90, v90
	v_rcp_f32_e32 v91, v91
	s_nop 0
	v_pk_mul_f32 v[84:85], v[98:99], v[90:91] op_sel_hi:[0,1]
	v_pk_mul_f32 v[80:81], v[80:81], v[84:85]
	s_nop 0
	v_cvt_pk_bf16_f32 v90, v80, v81
	v_pk_mul_f32 v[80:81], v[82:83], v[96:97] op_sel_hi:[1,0]
	s_nop 0
	v_exp_f32_e32 v80, v80
	v_exp_f32_e32 v81, v81
	s_nop 0
	v_pk_add_f32 v[80:81], v[80:81], 1.0 op_sel_hi:[1,0]
	s_nop 0
	v_rcp_f32_e32 v80, v80
	v_rcp_f32_e32 v81, v81
	s_nop 0
	v_pk_mul_f32 v[80:81], v[98:99], v[80:81] op_sel_hi:[0,1]
	v_pk_mul_f32 v[80:81], v[86:87], v[80:81]
	s_nop 0
	v_cvt_pk_bf16_f32 v91, v80, v81
	v_mad_u64_u32 v[80:81], s[6:7], v140, s14, 0
	v_mov_b32_e32 v82, v81
	v_mad_u64_u32 v[82:83], s[6:7], v141, s14, v[82:83]
	v_mov_b32_e32 v81, v82
	v_lshl_add_u64 v[80:81], v[80:81], 1, v[132:133]
	global_store_dwordx4 v[80:81], v[88:91], off
	v_fmamk_f32 v80, v150, 0x3a800000, v194
	v_rsq_f32_e32 v81, v80
	s_nop 0
	v_mul_f32_e32 v80, 0xbfb8aa3b, v81
	v_pk_mul_f32 v[84:85], v[72:73], v[80:81] op_sel_hi:[1,0]
	v_pk_mul_f32 v[74:75], v[74:75], v[80:81] op_sel_hi:[1,0]
	v_exp_f32_e32 v84, v84
	v_exp_f32_e32 v85, v85
	v_exp_f32_e32 v74, v74
	v_exp_f32_e32 v75, v75
	v_mul_f32_e32 v82, v81, v81
	v_pk_add_f32 v[84:85], v[84:85], 1.0 op_sel_hi:[1,0]
	v_pk_mul_f32 v[72:73], v[76:77], v[72:73]
	v_pk_add_f32 v[74:75], v[74:75], 1.0 op_sel_hi:[1,0]
	v_rcp_f32_e32 v84, v84
	v_rcp_f32_e32 v85, v85
	v_rcp_f32_e32 v74, v74
	v_rcp_f32_e32 v75, v75
	v_pk_mul_f32 v[76:77], v[82:83], v[84:85] op_sel_hi:[0,1]
	v_pk_mul_f32 v[72:73], v[72:73], v[76:77]
	v_pk_mul_f32 v[74:75], v[82:83], v[74:75] op_sel_hi:[0,1]
	v_pk_mul_f32 v[74:75], v[78:79], v[74:75]
	v_cvt_pk_bf16_f32 v72, v72, v73
	s_nop 0
	v_cvt_pk_bf16_f32 v73, v74, v75
	v_pk_mul_f32 v[74:75], v[64:65], v[80:81] op_sel_hi:[1,0]
	v_pk_mul_f32 v[64:65], v[68:69], v[64:65]
	v_exp_f32_e32 v74, v74
	v_exp_f32_e32 v75, v75
	s_nop 0
	v_pk_add_f32 v[74:75], v[74:75], 1.0 op_sel_hi:[1,0]
	s_nop 0
	v_rcp_f32_e32 v74, v74
	v_rcp_f32_e32 v75, v75
	s_nop 0
	v_pk_mul_f32 v[68:69], v[82:83], v[74:75] op_sel_hi:[0,1]
	v_pk_mul_f32 v[64:65], v[64:65], v[68:69]
	s_nop 0
	v_cvt_pk_bf16_f32 v74, v64, v65
	v_pk_mul_f32 v[64:65], v[66:67], v[80:81] op_sel_hi:[1,0]
	s_nop 0
	v_exp_f32_e32 v64, v64
	v_exp_f32_e32 v65, v65
	s_nop 0
	v_pk_add_f32 v[64:65], v[64:65], 1.0 op_sel_hi:[1,0]
	s_nop 0
	v_rcp_f32_e32 v64, v64
	v_rcp_f32_e32 v65, v65
	s_nop 0
	v_pk_mul_f32 v[64:65], v[82:83], v[64:65] op_sel_hi:[0,1]
	v_pk_mul_f32 v[64:65], v[70:71], v[64:65]
	s_nop 0
	v_cvt_pk_bf16_f32 v75, v64, v65
	v_mad_u64_u32 v[64:65], s[6:7], v138, s14, 0
	v_mov_b32_e32 v66, v65
	v_mad_u64_u32 v[66:67], s[6:7], v139, s14, v[66:67]
	v_mov_b32_e32 v65, v66
	v_lshl_add_u64 v[64:65], v[64:65], 1, v[132:133]
	global_store_dwordx4 v[64:65], v[72:75], off
	v_fmamk_f32 v64, v149, 0x3a800000, v194
	v_rsq_f32_e32 v65, v64
	s_nop 0
	v_mul_f32_e32 v64, 0xbfb8aa3b, v65
	v_pk_mul_f32 v[68:69], v[56:57], v[64:65] op_sel_hi:[1,0]
	v_pk_mul_f32 v[58:59], v[58:59], v[64:65] op_sel_hi:[1,0]
	v_exp_f32_e32 v68, v68
	v_exp_f32_e32 v69, v69
	v_exp_f32_e32 v58, v58
	v_exp_f32_e32 v59, v59
	v_mul_f32_e32 v66, v65, v65
	v_pk_add_f32 v[68:69], v[68:69], 1.0 op_sel_hi:[1,0]
	v_pk_mul_f32 v[56:57], v[60:61], v[56:57]
	v_pk_add_f32 v[58:59], v[58:59], 1.0 op_sel_hi:[1,0]
	v_rcp_f32_e32 v68, v68
	v_rcp_f32_e32 v69, v69
	v_rcp_f32_e32 v58, v58
	v_rcp_f32_e32 v59, v59
	v_pk_mul_f32 v[60:61], v[66:67], v[68:69] op_sel_hi:[0,1]
	v_pk_mul_f32 v[56:57], v[56:57], v[60:61]
	v_pk_mul_f32 v[58:59], v[66:67], v[58:59] op_sel_hi:[0,1]
	v_pk_mul_f32 v[58:59], v[62:63], v[58:59]
	v_cvt_pk_bf16_f32 v56, v56, v57
	s_nop 0
	v_cvt_pk_bf16_f32 v57, v58, v59
	v_pk_mul_f32 v[58:59], v[48:49], v[64:65] op_sel_hi:[1,0]
	v_pk_mul_f32 v[48:49], v[52:53], v[48:49]
	v_exp_f32_e32 v58, v58
	v_exp_f32_e32 v59, v59
	s_nop 0
	v_pk_add_f32 v[58:59], v[58:59], 1.0 op_sel_hi:[1,0]
	s_nop 0
	v_rcp_f32_e32 v58, v58
	v_rcp_f32_e32 v59, v59
	s_nop 0
	v_pk_mul_f32 v[52:53], v[66:67], v[58:59] op_sel_hi:[0,1]
	v_pk_mul_f32 v[48:49], v[48:49], v[52:53]
	s_nop 0
	v_cvt_pk_bf16_f32 v58, v48, v49
	v_pk_mul_f32 v[48:49], v[50:51], v[64:65] op_sel_hi:[1,0]
	s_nop 0
	v_exp_f32_e32 v48, v48
	v_exp_f32_e32 v49, v49
	s_nop 0
	v_pk_add_f32 v[48:49], v[48:49], 1.0 op_sel_hi:[1,0]
	s_nop 0
	v_rcp_f32_e32 v48, v48
	v_rcp_f32_e32 v49, v49
	s_nop 0
	v_pk_mul_f32 v[48:49], v[66:67], v[48:49] op_sel_hi:[0,1]
	v_pk_mul_f32 v[48:49], v[54:55], v[48:49]
	s_nop 0
	v_cvt_pk_bf16_f32 v59, v48, v49
	v_mad_u64_u32 v[48:49], s[6:7], v136, s14, 0
	v_mov_b32_e32 v50, v49
	v_mad_u64_u32 v[50:51], s[6:7], v137, s14, v[50:51]
	v_mov_b32_e32 v49, v50
	v_lshl_add_u64 v[48:49], v[48:49], 1, v[132:133]
	global_store_dwordx4 v[48:49], v[56:59], off
	v_fmamk_f32 v48, v148, 0x3a800000, v194
	v_rsq_f32_e32 v49, v48
	s_nop 0
	v_mul_f32_e32 v48, 0xbfb8aa3b, v49
	v_pk_mul_f32 v[52:53], v[40:41], v[48:49] op_sel_hi:[1,0]
	v_pk_mul_f32 v[42:43], v[42:43], v[48:49] op_sel_hi:[1,0]
	v_exp_f32_e32 v52, v52
	v_exp_f32_e32 v53, v53
	v_exp_f32_e32 v42, v42
	v_exp_f32_e32 v43, v43
	v_mul_f32_e32 v50, v49, v49
	v_pk_add_f32 v[52:53], v[52:53], 1.0 op_sel_hi:[1,0]
	v_pk_mul_f32 v[40:41], v[44:45], v[40:41]
	v_pk_add_f32 v[42:43], v[42:43], 1.0 op_sel_hi:[1,0]
	v_rcp_f32_e32 v52, v52
	v_rcp_f32_e32 v53, v53
	v_rcp_f32_e32 v42, v42
	v_rcp_f32_e32 v43, v43
	v_pk_mul_f32 v[44:45], v[50:51], v[52:53] op_sel_hi:[0,1]
	v_pk_mul_f32 v[40:41], v[40:41], v[44:45]
	v_pk_mul_f32 v[42:43], v[50:51], v[42:43] op_sel_hi:[0,1]
	v_pk_mul_f32 v[42:43], v[46:47], v[42:43]
	v_cvt_pk_bf16_f32 v40, v40, v41
	s_nop 0
	v_cvt_pk_bf16_f32 v41, v42, v43
	v_pk_mul_f32 v[42:43], v[32:33], v[48:49] op_sel_hi:[1,0]
	v_pk_mul_f32 v[32:33], v[36:37], v[32:33]
	v_exp_f32_e32 v42, v42
	v_exp_f32_e32 v43, v43
	s_nop 0
	v_pk_add_f32 v[42:43], v[42:43], 1.0 op_sel_hi:[1,0]
	s_nop 0
	v_rcp_f32_e32 v42, v42
	v_rcp_f32_e32 v43, v43
	s_nop 0
	v_pk_mul_f32 v[36:37], v[50:51], v[42:43] op_sel_hi:[0,1]
	v_pk_mul_f32 v[32:33], v[32:33], v[36:37]
	s_nop 0
	v_cvt_pk_bf16_f32 v42, v32, v33
	v_pk_mul_f32 v[32:33], v[34:35], v[48:49] op_sel_hi:[1,0]
	s_nop 0
	v_exp_f32_e32 v32, v32
	v_exp_f32_e32 v33, v33
	s_nop 0
	v_pk_add_f32 v[32:33], v[32:33], 1.0 op_sel_hi:[1,0]
	s_nop 0
	v_rcp_f32_e32 v32, v32
	v_rcp_f32_e32 v33, v33
	s_nop 0
	v_pk_mul_f32 v[32:33], v[50:51], v[32:33] op_sel_hi:[0,1]
	v_pk_mul_f32 v[32:33], v[38:39], v[32:33]
	s_nop 0
	v_cvt_pk_bf16_f32 v43, v32, v33
	v_mad_u64_u32 v[32:33], s[6:7], v134, s14, 0
	v_mov_b32_e32 v34, v33
	v_mad_u64_u32 v[34:35], s[6:7], v135, s14, v[34:35]
	v_mov_b32_e32 v33, v34
	v_lshl_add_u64 v[32:33], v[32:33], 1, v[132:133]
	global_store_dwordx4 v[32:33], v[40:43], off
	v_fmamk_f32 v32, v146, 0x3a800000, v194
	v_rsq_f32_e32 v33, v32
	s_nop 0
	v_mul_f32_e32 v32, 0xbfb8aa3b, v33
	v_pk_mul_f32 v[36:37], v[24:25], v[32:33] op_sel_hi:[1,0]
	v_pk_mul_f32 v[26:27], v[26:27], v[32:33] op_sel_hi:[1,0]
	v_exp_f32_e32 v36, v36
	v_exp_f32_e32 v37, v37
	v_exp_f32_e32 v26, v26
	v_exp_f32_e32 v27, v27
	v_mul_f32_e32 v34, v33, v33
	v_pk_add_f32 v[36:37], v[36:37], 1.0 op_sel_hi:[1,0]
	v_pk_mul_f32 v[24:25], v[28:29], v[24:25]
	v_pk_add_f32 v[26:27], v[26:27], 1.0 op_sel_hi:[1,0]
	v_rcp_f32_e32 v36, v36
	v_rcp_f32_e32 v37, v37
	v_rcp_f32_e32 v26, v26
	v_rcp_f32_e32 v27, v27
	v_pk_mul_f32 v[28:29], v[34:35], v[36:37] op_sel_hi:[0,1]
	v_pk_mul_f32 v[24:25], v[24:25], v[28:29]
	v_pk_mul_f32 v[26:27], v[34:35], v[26:27] op_sel_hi:[0,1]
	v_pk_mul_f32 v[26:27], v[30:31], v[26:27]
	v_cvt_pk_bf16_f32 v24, v24, v25
	s_nop 0
	v_cvt_pk_bf16_f32 v25, v26, v27
	v_pk_mul_f32 v[26:27], v[16:17], v[32:33] op_sel_hi:[1,0]
	v_pk_mul_f32 v[16:17], v[20:21], v[16:17]
	v_exp_f32_e32 v26, v26
	v_exp_f32_e32 v27, v27
	s_nop 0
	v_pk_add_f32 v[26:27], v[26:27], 1.0 op_sel_hi:[1,0]
	s_nop 0
	v_rcp_f32_e32 v26, v26
	v_rcp_f32_e32 v27, v27
	s_nop 0
	v_pk_mul_f32 v[20:21], v[34:35], v[26:27] op_sel_hi:[0,1]
	v_pk_mul_f32 v[16:17], v[16:17], v[20:21]
	s_nop 0
	v_cvt_pk_bf16_f32 v26, v16, v17
	v_pk_mul_f32 v[16:17], v[18:19], v[32:33] op_sel_hi:[1,0]
	s_nop 0
	v_exp_f32_e32 v16, v16
	v_exp_f32_e32 v17, v17
	s_nop 0
	v_pk_add_f32 v[16:17], v[16:17], 1.0 op_sel_hi:[1,0]
	s_nop 0
	v_rcp_f32_e32 v16, v16
	v_rcp_f32_e32 v17, v17
	s_nop 0
	v_pk_mul_f32 v[16:17], v[34:35], v[16:17] op_sel_hi:[0,1]
	v_pk_mul_f32 v[16:17], v[22:23], v[16:17]
	s_nop 0
	v_cvt_pk_bf16_f32 v27, v16, v17
	v_mad_u64_u32 v[16:17], s[6:7], v130, s14, 0
	v_mov_b32_e32 v18, v17
	v_mad_u64_u32 v[18:19], s[6:7], v131, s14, v[18:19]
	v_mov_b32_e32 v17, v18
	v_lshl_add_u64 v[16:17], v[16:17], 1, v[132:133]
	global_store_dwordx4 v[16:17], v[24:27], off
	v_fmamk_f32 v16, v147, 0x3a800000, v194
	v_rsq_f32_e32 v17, v16
	s_nop 0
	v_mul_f32_e32 v16, 0xbfb8aa3b, v17
	v_pk_mul_f32 v[20:21], v[8:9], v[16:17] op_sel_hi:[1,0]
	v_pk_mul_f32 v[10:11], v[10:11], v[16:17] op_sel_hi:[1,0]
	v_exp_f32_e32 v20, v20
	v_exp_f32_e32 v21, v21
	v_exp_f32_e32 v10, v10
	v_exp_f32_e32 v11, v11
	v_mul_f32_e32 v18, v17, v17
	v_pk_add_f32 v[20:21], v[20:21], 1.0 op_sel_hi:[1,0]
	v_pk_mul_f32 v[8:9], v[12:13], v[8:9]
	v_pk_add_f32 v[10:11], v[10:11], 1.0 op_sel_hi:[1,0]
	v_rcp_f32_e32 v20, v20
	v_rcp_f32_e32 v21, v21
	v_rcp_f32_e32 v10, v10
	v_rcp_f32_e32 v11, v11
	v_pk_mul_f32 v[12:13], v[18:19], v[20:21] op_sel_hi:[0,1]
	v_pk_mul_f32 v[8:9], v[8:9], v[12:13]
	v_pk_mul_f32 v[10:11], v[18:19], v[10:11] op_sel_hi:[0,1]
	v_pk_mul_f32 v[10:11], v[14:15], v[10:11]
	v_cvt_pk_bf16_f32 v8, v8, v9
	s_nop 0
	v_cvt_pk_bf16_f32 v9, v10, v11
	v_pk_mul_f32 v[10:11], v[0:1], v[16:17] op_sel_hi:[1,0]
	v_pk_mul_f32 v[0:1], v[4:5], v[0:1]
	v_exp_f32_e32 v10, v10
	v_exp_f32_e32 v11, v11
	s_nop 0
	v_pk_add_f32 v[10:11], v[10:11], 1.0 op_sel_hi:[1,0]
	s_nop 0
	v_rcp_f32_e32 v10, v10
	v_rcp_f32_e32 v11, v11
	s_nop 0
	v_pk_mul_f32 v[4:5], v[18:19], v[10:11] op_sel_hi:[0,1]
	v_pk_mul_f32 v[0:1], v[0:1], v[4:5]
	s_nop 0
	v_cvt_pk_bf16_f32 v10, v0, v1
	v_pk_mul_f32 v[0:1], v[2:3], v[16:17] op_sel_hi:[1,0]
	s_nop 0
	v_exp_f32_e32 v0, v0
	v_exp_f32_e32 v1, v1
	s_nop 0
	v_pk_add_f32 v[0:1], v[0:1], 1.0 op_sel_hi:[1,0]
	s_nop 0
	v_rcp_f32_e32 v0, v0
	v_rcp_f32_e32 v1, v1
	s_nop 0
	v_pk_mul_f32 v[0:1], v[18:19], v[0:1] op_sel_hi:[0,1]
	v_pk_mul_f32 v[0:1], v[6:7], v[0:1]
	s_nop 0
	v_cvt_pk_bf16_f32 v11, v0, v1
	v_mad_u64_u32 v[0:1], s[6:7], v128, s14, 0
	v_mov_b32_e32 v2, v1
	v_mad_u64_u32 v[2:3], s[6:7], v129, s14, v[2:3]
	v_mov_b32_e32 v1, v2
	v_lshl_add_u64 v[0:1], v[0:1], 1, v[132:133]
	global_store_dwordx4 v[0:1], v[8:11], off
	s_and_b64 vcc, exec, s[4:5]
	s_mov_b64 s[4:5], -1
	s_cbranch_vccnz .LBB0_604
